# control-word zeroing spread grid-stride over all workgroups (write-through stores) so workgroup 0 no longer starts P0 behind a 32-iteration loop, now that P0 is no longer gated by the grid sync; on to
# baseline (speedup 1.0000x reference)
; #define GAS __attribute__((address_space(1)))
; __global__ void __launch_bounds__(NWAVES * 64, 2) hybrid_fwd(const Args A) {
;     ...
;         if (blockIdx.x == 0) { GAS v4u* z = (GAS v4u*)(F.ws + WS_CTL); for (int i = F.tid; i < (int)(CTL_ZERO_BYTES / 16); i += NWAVES * 64) if (i < (int)(WS_PRM / 16) || i >= (int)((CW_SEAM * 4) / 16)) z[i] = (v4u){0u, 0u, 0u, 0u}; }
.Lcz_loop:
	v_cmp_gt_u32_e32 vcc, 0x4000, v8
	s_and_b64 exec, exec, vcc
	s_cbranch_execz .Lcz_done
	v_add_u32_e32 v9, 0xfffff000, v8
	v_cmp_le_u32_e32 vcc, 0x1000, v9
	s_and_saveexec_b64 s[10:11], vcc
	s_cbranch_execz .Lcz_skip
	v_lshlrev_b32_e32 v6, 4, v8
	v_mov_b32_e32 v7, 0
	v_lshl_add_u64 v[6:7], s[86:87], 0, v[6:7]
	global_store_dwordx4 v[6:7], v[2:5], off sc1

; #define GAS __attribute__((address_space(1)))
; __global__ void __launch_bounds__(NWAVES * 64, 2) hybrid_fwd(const Args A) {
;     ...
;         if (blockIdx.x == 0) { GAS v4u* z = (GAS v4u*)(F.ws + WS_CTL); for (int i = F.tid; i < (int)(CTL_ZERO_BYTES / 16); i += NWAVES * 64) if (i < (int)(WS_PRM / 16) || i >= (int)((CW_SEAM * 4) / 16)) z[i] = (v4u){0u, 0u, 0u, 0u}; }
;         grid.sync();
.Lcz_done:
	s_mov_b64 exec, s[4:5]
	v_lshrrev_b32_e32 v2, 20, v0
	v_lshrrev_b32_e32 v0, 10, v0
	v_or_b32_e32 v0, v0, v2
	s_movk_i32 s4, 0x3ff
	v_and_or_b32 v0, v0, s4, v1
	v_cmp_eq_u32_e32 vcc, 0, v0
	s_waitcnt vmcnt(0)
	s_barrier
	s_and_saveexec_b64 s[4:5], vcc
	s_cbranch_execz .LBB0_20
	s_waitcnt vmcnt(0)
	s_load_dwordx2 s[2:3], s[2:3], 0x58
	v_mov_b32_e32 v2, 0
	s_mov_b64 s[6:7], exec
	v_mbcnt_lo_u32_b32 v1, s6, 0
	v_mbcnt_hi_u32_b32 v1, s7, v1
	s_waitcnt lgkmcnt(0)
	global_load_dword v0, v2, s[2:3] offset:40
	v_cmp_eq_u32_e32 vcc, 0, v1
	s_and_saveexec_b64 s[8:9], vcc
	s_cbranch_execz .LBB0_13
	s_bcnt1_i32_b64 s6, s[6:7]
	v_mov_b32_e32 v3, s6
	global_atomic_add v3, v2, v3, s[2:3] offset:32 sc0
